# v33 + nontemporal row loads in the diff-norm phase (P7)
# baseline (speedup 1.0000x reference)
.LBB0_1457:
	v_add_co_u32_e32 v40, vcc, 0x58401000, v34
	v_lshl_add_u64 v[42:43], v[34:35], 0, s[6:7]
	v_lshl_add_u64 v[44:45], v[34:35], 0, s[10:11]
	v_addc_co_u32_e32 v41, vcc, 0, v35, vcc
	global_load_dwordx4 v[48:51], v[42:43], off offset:48 nt
	global_load_dwordx4 v[52:55], v[44:45], off offset:48 nt
	global_load_dwordx4 v[56:59], v[42:43], off offset:16 nt
	global_load_dwordx4 v[60:63], v[44:45], off offset:16 nt
	global_load_dwordx4 v[64:67], v[42:43], off offset:32 nt
	global_load_dwordx4 v[68:71], v[44:45], off offset:32 nt
	s_nop 0
	global_load_dwordx4 v[42:45], v[40:41], off nt
	global_load_dwordx4 v[72:75], v[40:41], off offset:512 nt
	s_waitcnt vmcnt(0)
	s_add_i32 s15, s15, s33
	v_lshl_add_u64 v[38:39], v[34:35], 0, v[36:37]
	v_lshl_add_u64 v[34:35], v[34:35], 0, s[4:5]
	s_cmpk_lt_i32 s15, 0x4000
	s_waitcnt vmcnt(7)
	v_lshlrev_b32_e32 v41, 16, v49
	v_lshlrev_b32_e32 v40, 16, v48
	s_waitcnt vmcnt(6)
	v_lshlrev_b32_e32 v77, 16, v53
	v_lshlrev_b32_e32 v76, 16, v52
	v_lshlrev_b32_e32 v79, 16, v51
	v_lshlrev_b32_e32 v78, 16, v50
	v_lshlrev_b32_e32 v81, 16, v55
	v_lshlrev_b32_e32 v80, 16, v54
	v_and_b32_e32 v51, 0xffff0000, v51
	v_and_b32_e32 v50, 0xffff0000, v50
	v_and_b32_e32 v55, 0xffff0000, v55
	v_and_b32_e32 v54, 0xffff0000, v54
	v_and_b32_e32 v49, 0xffff0000, v49
	v_and_b32_e32 v48, 0xffff0000, v48
	v_and_b32_e32 v53, 0xffff0000, v53
	v_and_b32_e32 v52, 0xffff0000, v52
	v_pk_fma_f32 v[40:41], v[0:1], v[76:77], v[40:41] neg_lo:[1,0,0] neg_hi:[1,0,0]
	v_pk_fma_f32 v[50:51], v[0:1], v[54:55], v[50:51] neg_lo:[1,0,0] neg_hi:[1,0,0]
	s_waitcnt vmcnt(1)
	v_lshlrev_b32_e32 v55, 16, v43
	v_lshlrev_b32_e32 v54, 16, v42
	s_waitcnt vmcnt(0)
	v_lshlrev_b32_e32 v77, 16, v73
	v_lshlrev_b32_e32 v76, 16, v72
	v_and_b32_e32 v43, 0xffff0000, v43
	v_and_b32_e32 v42, 0xffff0000, v42
	v_and_b32_e32 v73, 0xffff0000, v73
	v_and_b32_e32 v72, 0xffff0000, v72
	v_lshlrev_b32_e32 v83, 16, v57
	v_lshlrev_b32_e32 v82, 16, v56
	v_lshlrev_b32_e32 v85, 16, v61
	v_lshlrev_b32_e32 v84, 16, v60
	v_and_b32_e32 v57, 0xffff0000, v57
	v_and_b32_e32 v56, 0xffff0000, v56
	v_and_b32_e32 v61, 0xffff0000, v61
	v_and_b32_e32 v60, 0xffff0000, v60
	v_lshlrev_b32_e32 v87, 16, v59
	v_lshlrev_b32_e32 v86, 16, v58
	v_lshlrev_b32_e32 v89, 16, v63
	v_lshlrev_b32_e32 v88, 16, v62
	v_pk_fma_f32 v[48:49], v[0:1], v[52:53], v[48:49] neg_lo:[1,0,0] neg_hi:[1,0,0]
	v_pk_fma_f32 v[52:53], v[0:1], v[80:81], v[78:79] neg_lo:[1,0,0] neg_hi:[1,0,0]
	v_lshlrev_b32_e32 v79, 16, v45
	v_lshlrev_b32_e32 v78, 16, v44
	v_lshlrev_b32_e32 v81, 16, v75
	v_lshlrev_b32_e32 v80, 16, v74
	v_and_b32_e32 v45, 0xffff0000, v45
	v_and_b32_e32 v44, 0xffff0000, v44
	v_and_b32_e32 v75, 0xffff0000, v75
	v_and_b32_e32 v74, 0xffff0000, v74
	v_pk_fma_f32 v[42:43], v[0:1], v[72:73], v[42:43] neg_lo:[1,0,0] neg_hi:[1,0,0]
	v_pk_fma_f32 v[56:57], v[0:1], v[60:61], v[56:57] neg_lo:[1,0,0] neg_hi:[1,0,0]
	v_pk_fma_f32 v[60:61], v[0:1], v[88:89], v[86:87] neg_lo:[1,0,0] neg_hi:[1,0,0]
	v_pk_fma_f32 v[54:55], v[0:1], v[76:77], v[54:55] neg_lo:[1,0,0] neg_hi:[1,0,0]
	v_pk_fma_f32 v[44:45], v[0:1], v[74:75], v[44:45] neg_lo:[1,0,0] neg_hi:[1,0,0]
	v_pk_mul_f32 v[86:87], v[42:43], v[42:43]
	v_pk_fma_f32 v[72:73], v[0:1], v[80:81], v[78:79] neg_lo:[1,0,0] neg_hi:[1,0,0]
	v_pk_mul_f32 v[88:89], v[44:45], v[44:45]
	v_pk_fma_f32 v[86:87], v[54:55], v[54:55], v[86:87]
	v_pk_fma_f32 v[88:89], v[72:73], v[72:73], v[88:89]
	v_add_f32_e32 v86, v86, v87
	v_and_b32_e32 v59, 0xffff0000, v59
	v_and_b32_e32 v58, 0xffff0000, v58
	v_and_b32_e32 v63, 0xffff0000, v63
	v_and_b32_e32 v62, 0xffff0000, v62
	v_pk_fma_f32 v[82:83], v[0:1], v[84:85], v[82:83] neg_lo:[1,0,0] neg_hi:[1,0,0]
	v_pk_mul_f32 v[74:75], v[56:57], v[56:57]
	v_add_f32_e32 v86, v88, v86
	v_pk_fma_f32 v[58:59], v[0:1], v[62:63], v[58:59] neg_lo:[1,0,0] neg_hi:[1,0,0]
	v_pk_fma_f32 v[74:75], v[82:83], v[82:83], v[74:75]
	v_add_f32_e32 v86, v89, v86
	v_lshlrev_b32_e32 v91, 16, v65
	v_lshlrev_b32_e32 v90, 16, v64
	v_lshlrev_b32_e32 v93, 16, v69
	v_lshlrev_b32_e32 v92, 16, v68
	v_and_b32_e32 v65, 0xffff0000, v65
	v_and_b32_e32 v64, 0xffff0000, v64
	v_and_b32_e32 v69, 0xffff0000, v69
	v_and_b32_e32 v68, 0xffff0000, v68
	v_pk_mul_f32 v[76:77], v[58:59], v[58:59]
	v_add_f32_e32 v74, v74, v86
	v_pk_fma_f32 v[64:65], v[0:1], v[68:69], v[64:65] neg_lo:[1,0,0] neg_hi:[1,0,0]
	v_pk_fma_f32 v[76:77], v[60:61], v[60:61], v[76:77]
	v_add_f32_e32 v74, v75, v74
	v_lshlrev_b32_e32 v95, 16, v67
	v_lshlrev_b32_e32 v94, 16, v66
	v_lshlrev_b32_e32 v97, 16, v71
	v_lshlrev_b32_e32 v96, 16, v70
	v_and_b32_e32 v67, 0xffff0000, v67
	v_and_b32_e32 v66, 0xffff0000, v66
	v_and_b32_e32 v71, 0xffff0000, v71
	v_and_b32_e32 v70, 0xffff0000, v70
	v_pk_fma_f32 v[62:63], v[0:1], v[92:93], v[90:91] neg_lo:[1,0,0] neg_hi:[1,0,0]
	v_pk_mul_f32 v[78:79], v[64:65], v[64:65]
	v_add_f32_e32 v74, v76, v74
	v_pk_fma_f32 v[66:67], v[0:1], v[70:71], v[66:67] neg_lo:[1,0,0] neg_hi:[1,0,0]
	v_pk_fma_f32 v[78:79], v[62:63], v[62:63], v[78:79]
	v_add_f32_e32 v74, v77, v74
	v_pk_fma_f32 v[68:69], v[0:1], v[96:97], v[94:95] neg_lo:[1,0,0] neg_hi:[1,0,0]
	v_pk_mul_f32 v[80:81], v[66:67], v[66:67]
	v_add_f32_e32 v74, v78, v74
	v_pk_fma_f32 v[80:81], v[68:69], v[68:69], v[80:81]
	v_add_f32_e32 v74, v79, v74
	v_pk_mul_f32 v[70:71], v[48:49], v[48:49]
	v_add_f32_e32 v74, v80, v74
	v_pk_fma_f32 v[70:71], v[40:41], v[40:41], v[70:71]
	v_add_f32_e32 v74, v81, v74
	v_pk_mul_f32 v[84:85], v[50:51], v[50:51]
	v_add_f32_e32 v70, v70, v74
	v_pk_fma_f32 v[84:85], v[52:53], v[52:53], v[84:85]
	v_add_f32_e32 v70, v71, v70
	v_add_f32_e32 v70, v84, v70
	v_add_f32_e32 v70, v85, v70
	ds_bpermute_b32 v71, v204, v70
	s_waitcnt lgkmcnt(0)
	v_add_f32_e32 v70, v70, v71
	ds_bpermute_b32 v71, v205, v70
	s_waitcnt lgkmcnt(0)
	v_add_f32_e32 v70, v70, v71
	ds_bpermute_b32 v71, v206, v70
	s_waitcnt lgkmcnt(0)
	v_add_f32_e32 v70, v70, v71
	v_fmamk_f32 v70, v70, 0x3b800000, v46
	v_mul_f32_e32 v71, 0x4f800000, v70
	v_cmp_gt_f32_e32 vcc, s13, v70
	s_nop 1
	v_cndmask_b32_e32 v70, v70, v71, vcc
	v_sqrt_f32_e32 v71, v70
	s_nop 0
	v_add_u32_e32 v74, -1, v71
	v_add_u32_e32 v75, 1, v71
	v_fma_f32 v76, -v74, v71, v70
	v_fma_f32 v77, -v75, v71, v70
	v_cmp_ge_f32_e64 s[2:3], 0, v76
	s_nop 1
	v_cndmask_b32_e64 v71, v71, v74, s[2:3]
	v_cmp_lt_f32_e64 s[2:3], 0, v77
	s_nop 1
	v_cndmask_b32_e64 v71, v71, v75, s[2:3]
	v_mul_f32_e32 v74, 0x37800000, v71
	v_cndmask_b32_e32 v71, v71, v74, vcc
	v_cmp_class_f32_e32 vcc, v70, v47
	s_nop 1
	v_cndmask_b32_e32 v70, v71, v70, vcc
	v_div_scale_f32 v71, s[0:1], v70, v70, 1.0
	v_rcp_f32_e32 v75, v71
	v_div_scale_f32 v74, vcc, 1.0, v70, 1.0
	v_fma_f32 v76, -v71, v75, 1.0
	v_fmac_f32_e32 v75, v76, v75
	v_mul_f32_e32 v76, v74, v75
	v_fma_f32 v77, -v71, v76, v74
	v_fmac_f32_e32 v76, v77, v75
	v_fma_f32 v71, -v71, v76, v74
	v_div_fmas_f32 v71, v71, v75, v76
	v_div_fixup_f32 v70, v71, v70, 1.0
	v_pk_mul_f32 v[54:55], v[54:55], v[70:71] op_sel_hi:[1,0]
	v_pk_mul_f32 v[42:43], v[42:43], v[70:71] op_sel_hi:[1,0]
	v_pk_mul_f32 v[72:73], v[72:73], v[70:71] op_sel_hi:[1,0]
	v_pk_mul_f32 v[44:45], v[44:45], v[70:71] op_sel_hi:[1,0]
	v_pk_mul_f32 v[74:75], v[82:83], v[70:71] op_sel_hi:[1,0]
	v_pk_mul_f32 v[56:57], v[56:57], v[70:71] op_sel_hi:[1,0]
	v_pk_mul_f32 v[60:61], v[60:61], v[70:71] op_sel_hi:[1,0]
	v_pk_mul_f32 v[58:59], v[58:59], v[70:71] op_sel_hi:[1,0]
	v_pk_mul_f32 v[62:63], v[62:63], v[70:71] op_sel_hi:[1,0]
	v_pk_mul_f32 v[64:65], v[64:65], v[70:71] op_sel_hi:[1,0]
	v_pk_mul_f32 v[68:69], v[68:69], v[70:71] op_sel_hi:[1,0]
	v_pk_mul_f32 v[66:67], v[66:67], v[70:71] op_sel_hi:[1,0]
	v_pk_mul_f32 v[40:41], v[40:41], v[70:71] op_sel_hi:[1,0]
	v_pk_mul_f32 v[48:49], v[48:49], v[70:71] op_sel_hi:[1,0]
	v_pk_mul_f32 v[52:53], v[52:53], v[70:71] op_sel_hi:[1,0]
	v_pk_mul_f32 v[50:51], v[50:51], v[70:71] op_sel_hi:[1,0]
	v_pk_mul_f32 v[54:55], v[2:3], v[54:55]
	v_pk_mul_f32 v[42:43], v[4:5], v[42:43]
	v_pk_mul_f32 v[70:71], v[6:7], v[72:73]
	v_pk_mul_f32 v[44:45], v[8:9], v[44:45]
	v_pk_mul_f32 v[72:73], v[10:11], v[74:75]
	v_pk_mul_f32 v[60:61], v[14:15], v[60:61]
	v_pk_mul_f32 v[62:63], v[18:19], v[62:63]
	v_pk_mul_f32 v[68:69], v[22:23], v[68:69]
	v_pk_mul_f32 v[40:41], v[26:27], v[40:41]
	v_pk_mul_f32 v[48:49], v[28:29], v[48:49]
	v_pk_mul_f32 v[52:53], v[30:31], v[52:53]
	v_pk_mul_f32 v[50:51], v[32:33], v[50:51]
	v_bfe_u32 v74, v45, 16, 1
	v_bfe_u32 v75, v44, 16, 1
	v_bfe_u32 v76, v43, 16, 1
	v_bfe_u32 v77, v42, 16, 1
	v_bfe_u32 v78, v54, 16, 1
	v_bfe_u32 v79, v55, 16, 1
	v_bfe_u32 v80, v70, 16, 1
	v_bfe_u32 v81, v71, 16, 1
	v_pk_mul_f32 v[56:57], v[12:13], v[56:57]
	v_pk_mul_f32 v[58:59], v[16:17], v[58:59]
	v_pk_mul_f32 v[64:65], v[20:21], v[64:65]
	v_pk_mul_f32 v[66:67], v[24:25], v[66:67]
	v_bfe_u32 v86, v72, 16, 1
	v_bfe_u32 v87, v73, 16, 1
	v_bfe_u32 v88, v60, 16, 1
	v_bfe_u32 v89, v61, 16, 1
	v_bfe_u32 v94, v62, 16, 1
	v_bfe_u32 v95, v63, 16, 1
	v_bfe_u32 v96, v68, 16, 1
	v_bfe_u32 v97, v69, 16, 1
	v_bfe_u32 v98, v51, 16, 1
	v_bfe_u32 v99, v50, 16, 1
	v_bfe_u32 v100, v49, 16, 1
	v_bfe_u32 v101, v48, 16, 1
	v_bfe_u32 v102, v40, 16, 1
	v_bfe_u32 v103, v41, 16, 1
	v_bfe_u32 v104, v52, 16, 1
	v_bfe_u32 v105, v53, 16, 1
	v_add3_u32 v77, v42, v77, s14
	v_add3_u32 v76, v43, v76, s14
	v_add3_u32 v42, v44, v75, s14
	v_add3_u32 v43, v45, v74, s14
	v_add3_u32 v44, v71, v81, s14
	v_add3_u32 v45, v70, v80, s14
	v_add3_u32 v55, v55, v79, s14
	v_add3_u32 v54, v54, v78, s14
	v_bfe_u32 v82, v59, 16, 1
	v_bfe_u32 v83, v58, 16, 1
	v_bfe_u32 v84, v57, 16, 1
	v_bfe_u32 v85, v56, 16, 1
	v_bfe_u32 v90, v67, 16, 1
	v_bfe_u32 v91, v66, 16, 1
	v_bfe_u32 v92, v65, 16, 1
	v_bfe_u32 v93, v64, 16, 1
	v_add3_u32 v61, v61, v89, s14
	v_add3_u32 v60, v60, v88, s14
	v_add3_u32 v70, v73, v87, s14
	v_add3_u32 v71, v72, v86, s14
	v_add3_u32 v69, v69, v97, s14
	v_add3_u32 v68, v68, v96, s14
	v_add3_u32 v63, v63, v95, s14
	v_add3_u32 v62, v62, v94, s14
	v_add3_u32 v72, v48, v101, s14
	v_add3_u32 v73, v49, v100, s14
	v_add3_u32 v74, v50, v99, s14
	v_add3_u32 v75, v51, v98, s14
	v_add3_u32 v48, v53, v105, s14
	v_add3_u32 v49, v52, v104, s14
	v_add3_u32 v41, v41, v103, s14
	v_add3_u32 v40, v40, v102, s14
	v_lshrrev_b32_e32 v50, 16, v54
	v_lshrrev_b32_e32 v51, 16, v55
	v_lshrrev_b32_e32 v45, 16, v45
	v_lshrrev_b32_e32 v44, 16, v44
	v_add3_u32 v56, v56, v85, s14
	v_add3_u32 v57, v57, v84, s14
	v_add3_u32 v58, v58, v83, s14
	v_add3_u32 v59, v59, v82, s14
	v_add3_u32 v64, v64, v93, s14
	v_add3_u32 v65, v65, v92, s14
	v_add3_u32 v66, v66, v91, s14
	v_add3_u32 v67, v67, v90, s14
	v_lshrrev_b32_e32 v52, 16, v71
	v_lshrrev_b32_e32 v53, 16, v70
	v_lshrrev_b32_e32 v54, 16, v60
	v_lshrrev_b32_e32 v55, 16, v61
	v_lshrrev_b32_e32 v60, 16, v62
	v_lshrrev_b32_e32 v61, 16, v63
	v_lshrrev_b32_e32 v62, 16, v68
	v_lshrrev_b32_e32 v63, 16, v69
	v_lshrrev_b32_e32 v68, 16, v40
	v_lshrrev_b32_e32 v69, 16, v41
	v_lshrrev_b32_e32 v70, 16, v49
	v_lshrrev_b32_e32 v71, 16, v48
	v_and_or_b32 v43, v43, s12, v44
	v_and_or_b32 v42, v42, s12, v45
	v_and_or_b32 v41, v76, s12, v51
	v_and_or_b32 v40, v77, s12, v50
	v_and_or_b32 v51, v59, s12, v55
	v_and_or_b32 v50, v58, s12, v54
	v_and_or_b32 v49, v57, s12, v53
	v_and_or_b32 v48, v56, s12, v52
	v_and_or_b32 v55, v67, s12, v63
	v_and_or_b32 v54, v66, s12, v62
	v_and_or_b32 v53, v65, s12, v61
	v_and_or_b32 v52, v64, s12, v60
	v_and_or_b32 v59, v75, s12, v71
	v_and_or_b32 v58, v74, s12, v70
	v_and_or_b32 v57, v73, s12, v69
	v_and_or_b32 v56, v72, s12, v68
	global_store_dwordx4 v[38:39], v[40:43], off offset:-32
	global_store_dwordx4 v[38:39], v[48:51], off offset:-16
	global_store_dwordx4 v[38:39], v[52:55], off
	global_store_dwordx4 v[38:39], v[56:59], off offset:16
	s_cbranch_scc1 .LBB0_1457
